# ML helper step B: 16 masked exp-scaled score rows computed straight-line (sMi preloaded as 4x b128, no divergent branches)
# baseline (speedup 1.0000x reference)
; DI bf16_t f2bf(float a) { return (bf16_t)(pk2(a, 0.f) & 0xffffu); }
; #define MFMA32(a, b, c) __builtin_amdgcn_mfma_f32_32x32x16_bf16((a), (b), (c), 0, 0, 0)
; DI int crow(int reg, int hh) { return (reg & 3) + 8 * (reg >> 2) + 4 * hh; }
; template <bool CONS>
; DI void ml_chain_role(const Params& p, unsigned char* smem, int dir, int b, int h) {
;     ...
;             for (int s = 0; s < 8; ++s) { const bf16x8 a = load_nat(sQ, ST, 32 * ti + r, 16 * s + 8 * hh), bb = load_nat(sK, ST, 32 * tj + r, 16 * s + 8 * hh); acc = MFMA32(a, bb, acc); }
;             const int j = 32 * tj + r; const float aj = sAj[j];
; #pragma unroll
;             for (int i16 = 0; i16 < 16; ++i16) { const int i = 32 * ti + crow(i16, hh); sS[i * STT + j] = f2bf(i >= j ? acc[i16] * KSC * __expf(aj - sMi[i]) : 0.f); }
.LBB0_438:
	s_waitcnt lgkmcnt(0)
	s_barrier
	v_and_b32_e32 v50, 31, v65
	v_ashrrev_i32_e32 v82, 5, v65
	s_setprio 2
	v_or_b32_e32 v0, s48, v50
	v_mul_u32_u24_e32 v0, 0x110, v0
	v_lshlrev_b32_e32 v4, 4, v82
	v_add3_u32 v83, 0, v0, v4
	ds_read_b128 v[0:3], v83
	v_or_b32_e32 v53, s49, v50
	v_mul_u32_u24_e32 v5, 0x110, v53
	v_add3_u32 v84, 0, v5, v4
	ds_read_b128 v[4:7], v84 offset:17408
	ds_read_b128 v[66:69], v83 offset:32
	ds_read_b128 v[70:73], v84 offset:17440
	s_waitcnt lgkmcnt(2)
	v_mfma_f32_32x32x16_bf16 v[0:15], v[0:3], v[4:7], 0
	s_waitcnt lgkmcnt(0)
	v_mfma_f32_32x32x16_bf16 v[0:15], v[66:69], v[70:73], v[0:15]
	ds_read_b128 v[66:69], v83 offset:64
	ds_read_b128 v[70:73], v84 offset:17472
	ds_read_b128 v[74:77], v83 offset:96
	ds_read_b128 v[78:81], v84 offset:17504
	s_waitcnt lgkmcnt(2)
	v_mfma_f32_32x32x16_bf16 v[0:15], v[66:69], v[70:73], v[0:15]
	s_waitcnt lgkmcnt(0)
	v_mfma_f32_32x32x16_bf16 v[0:15], v[74:77], v[78:81], v[0:15]
	ds_read_b128 v[66:69], v83 offset:128
	ds_read_b128 v[70:73], v84 offset:17536
	ds_read_b128 v[74:77], v83 offset:160
	ds_read_b128 v[78:81], v84 offset:17568
	s_waitcnt lgkmcnt(2)
	v_mfma_f32_32x32x16_bf16 v[0:15], v[66:69], v[70:73], v[0:15]
	s_waitcnt lgkmcnt(0)
	v_mfma_f32_32x32x16_bf16 v[0:15], v[74:77], v[78:81], v[0:15]
	ds_read_b128 v[66:69], v83 offset:192
	ds_read_b128 v[70:73], v84 offset:17600
	ds_read_b128 v[74:77], v83 offset:224
	ds_read_b128 v[78:81], v84 offset:17632
	s_waitcnt lgkmcnt(2)
	v_mfma_f32_32x32x16_bf16 v[0:15], v[66:69], v[70:73], v[0:15]
	v_lshl_add_u32 v66, v53, 2, s77
	ds_read_b32 v66, v66
	v_lshl_add_u32 v68, v82, 2, s48
	v_lshl_add_u32 v67, v68, 2, s77
	ds_read_b128 v[224:227], v67 offset:256
	ds_read_b128 v[228:231], v67 offset:288
	ds_read_b128 v[232:235], v67 offset:320
	ds_read_b128 v[236:239], v67 offset:352
	v_lshl_add_u32 v240, v53, 1, s73
	v_mul_lo_u32 v71, v68, s74
	v_add_u32_e32 v240, v240, v71
	v_sub_u32_e32 v241, v53, v68
	s_waitcnt lgkmcnt(5)
	v_mfma_f32_32x32x16_bf16 v[0:15], v[74:77], v[78:81], v[0:15]
	s_waitcnt lgkmcnt(0)
	v_sub_f32_e32 v224, v66, v224
	v_sub_f32_e32 v225, v66, v225
	v_sub_f32_e32 v226, v66, v226
	v_sub_f32_e32 v227, v66, v227
	v_sub_f32_e32 v228, v66, v228
	v_sub_f32_e32 v229, v66, v229
	v_sub_f32_e32 v230, v66, v230
	v_sub_f32_e32 v231, v66, v231
	v_sub_f32_e32 v232, v66, v232
	v_sub_f32_e32 v233, v66, v233
	v_sub_f32_e32 v234, v66, v234
	v_sub_f32_e32 v235, v66, v235
	v_sub_f32_e32 v236, v66, v236
	v_sub_f32_e32 v237, v66, v237
	v_sub_f32_e32 v238, v66, v238
	v_sub_f32_e32 v239, v66, v239
	v_mul_f32_e32 v224, 0x3fb8aa3b, v224
	v_mul_f32_e32 v225, 0x3fb8aa3b, v225
	v_mul_f32_e32 v226, 0x3fb8aa3b, v226
	v_mul_f32_e32 v227, 0x3fb8aa3b, v227
	v_mul_f32_e32 v228, 0x3fb8aa3b, v228
	v_mul_f32_e32 v229, 0x3fb8aa3b, v229
	v_mul_f32_e32 v230, 0x3fb8aa3b, v230
	v_mul_f32_e32 v231, 0x3fb8aa3b, v231
	v_mul_f32_e32 v232, 0x3fb8aa3b, v232
	v_mul_f32_e32 v233, 0x3fb8aa3b, v233
	v_mul_f32_e32 v234, 0x3fb8aa3b, v234
	v_mul_f32_e32 v235, 0x3fb8aa3b, v235
	v_mul_f32_e32 v236, 0x3fb8aa3b, v236
	v_mul_f32_e32 v237, 0x3fb8aa3b, v237
	v_mul_f32_e32 v238, 0x3fb8aa3b, v238
	v_mul_f32_e32 v239, 0x3fb8aa3b, v239
	v_exp_f32_e32 v224, v224
	v_exp_f32_e32 v225, v225
	v_exp_f32_e32 v226, v226
	v_exp_f32_e32 v227, v227
	v_exp_f32_e32 v228, v228
	v_exp_f32_e32 v229, v229
	v_exp_f32_e32 v230, v230
	v_exp_f32_e32 v231, v231
	v_exp_f32_e32 v232, v232
	v_exp_f32_e32 v233, v233
	v_exp_f32_e32 v234, v234
	v_exp_f32_e32 v235, v235
	v_exp_f32_e32 v236, v236
	v_exp_f32_e32 v237, v237
	v_exp_f32_e32 v238, v238
	v_exp_f32_e32 v239, v239
	v_mul_f32_e32 v0, 0x3db504f3, v0
	v_mul_f32_e32 v1, 0x3db504f3, v1
	v_mul_f32_e32 v2, 0x3db504f3, v2
	v_mul_f32_e32 v3, 0x3db504f3, v3
	v_mul_f32_e32 v4, 0x3db504f3, v4
	v_mul_f32_e32 v5, 0x3db504f3, v5
	v_mul_f32_e32 v6, 0x3db504f3, v6
	v_mul_f32_e32 v7, 0x3db504f3, v7
	v_mul_f32_e32 v8, 0x3db504f3, v8
	v_mul_f32_e32 v9, 0x3db504f3, v9
	v_mul_f32_e32 v10, 0x3db504f3, v10
	v_mul_f32_e32 v11, 0x3db504f3, v11
	v_mul_f32_e32 v12, 0x3db504f3, v12
	v_mul_f32_e32 v13, 0x3db504f3, v13
	v_mul_f32_e32 v14, 0x3db504f3, v14
	v_mul_f32_e32 v15, 0x3db504f3, v15
	v_mul_f32_e32 v0, v0, v224
	v_mul_f32_e32 v1, v1, v225
	v_mul_f32_e32 v2, v2, v226
	v_mul_f32_e32 v3, v3, v227
	v_mul_f32_e32 v4, v4, v228
	v_mul_f32_e32 v5, v5, v229
	v_mul_f32_e32 v6, v6, v230
	v_mul_f32_e32 v7, v7, v231
	v_mul_f32_e32 v8, v8, v232
	v_mul_f32_e32 v9, v9, v233
	v_mul_f32_e32 v10, v10, v234
	v_mul_f32_e32 v11, v11, v235
	v_mul_f32_e32 v12, v12, v236
	v_mul_f32_e32 v13, v13, v237
	v_mul_f32_e32 v14, v14, v238
	v_mul_f32_e32 v15, v15, v239
	v_cmp_ge_i32_e32 vcc, 0, v241
	s_nop 1
	v_cndmask_b32_e32 v0, 0, v0, vcc
	v_cmp_ge_i32_e32 vcc, 1, v241
	v_cvt_pk_bf16_f32 v0, v0, s0
	ds_write_b16 v240, v0
	v_cndmask_b32_e32 v1, 0, v1, vcc
	v_cmp_ge_i32_e32 vcc, 2, v241
	v_cvt_pk_bf16_f32 v1, v1, s0
	ds_write_b16 v240, v1 offset:144
	v_cndmask_b32_e32 v2, 0, v2, vcc
	v_cmp_ge_i32_e32 vcc, 3, v241
	v_cvt_pk_bf16_f32 v2, v2, s0
	ds_write_b16 v240, v2 offset:288
	v_cndmask_b32_e32 v3, 0, v3, vcc
	v_cmp_ge_i32_e32 vcc, 8, v241
	v_cvt_pk_bf16_f32 v3, v3, s0
	ds_write_b16 v240, v3 offset:432
	v_cndmask_b32_e32 v4, 0, v4, vcc
	v_cmp_ge_i32_e32 vcc, 9, v241
	v_cvt_pk_bf16_f32 v4, v4, s0
	ds_write_b16 v240, v4 offset:1152
	v_cndmask_b32_e32 v5, 0, v5, vcc
	v_cmp_ge_i32_e32 vcc, 10, v241
	v_cvt_pk_bf16_f32 v5, v5, s0
	ds_write_b16 v240, v5 offset:1296
	v_cndmask_b32_e32 v6, 0, v6, vcc
	v_cmp_ge_i32_e32 vcc, 11, v241
	v_cvt_pk_bf16_f32 v6, v6, s0
	ds_write_b16 v240, v6 offset:1440
	v_cndmask_b32_e32 v7, 0, v7, vcc
	v_cmp_ge_i32_e32 vcc, 16, v241
	v_cvt_pk_bf16_f32 v7, v7, s0
	ds_write_b16 v240, v7 offset:1584
; DI unsigned pk2(float a, float b) { f32x2 v = {a, b}; bf16x2_t r = __builtin_convertvector(v, bf16x2_t); return __builtin_bit_cast(unsigned, r); }
; DI bf16_t f2bf(float a) { return (bf16_t)(pk2(a, 0.f) & 0xffffu); }
; DI float bflo(unsigned u) { return __uint_as_float(u << 16); }
; DI float bfhi(unsigned u) { return __uint_as_float(u & 0xffff0000u); }
; DI int crow(int reg, int hh) { return (reg & 3) + 8 * (reg >> 2) + 4 * hh; }
; template <bool CONS>
; DI void ml_chain_role(const Params& p, unsigned char* smem, int dir, int b, int h) {
;     ...
;             for (int i16 = 0; i16 < 16; ++i16) { const int i = 32 * ti + crow(i16, hh); sS[i * STT + j] = f2bf(i >= j ? acc[i16] * KSC * __expf(aj - sMi[i]) : 0.f); }
;             const int t = tid - 256;
;             {
; #pragma unroll
;               for (int it = 0; it < 2; ++it) { const int item = t + 256 * it, i2 = item & 31, c8 = item >> 5;
;                   const float da = sWtok[2 * i2], db = sWtok[2 * i2 + 1];
;                   const bf16_t* srcp = sK + (2 * i2) * ST + c8 * 8;
;                   const u32x4 ka = *(const u32x4*)srcp, kb = *(const u32x4*)(srcp + ST);
;                   unsigned* d = (unsigned*)(sKT + (8 * c8) * STT) + i2;
;                   d[0 * (STT / 2)] = pk2(bflo(ka.x) * da, bflo(kb.x) * db); d[1 * (STT / 2)] = pk2(bfhi(ka.x) * da, bfhi(kb.x) * db);
;                   d[2 * (STT / 2)] = pk2(bflo(ka.y) * da, bflo(kb.y) * db); d[3 * (STT / 2)] = pk2(bfhi(ka.y) * da, bfhi(kb.y) * db);
;                   d[4 * (STT / 2)] = pk2(bflo(ka.z) * da, bflo(kb.z) * db); d[5 * (STT / 2)] = pk2(bfhi(ka.z) * da, bfhi(kb.z) * db);
;                   d[6 * (STT / 2)] = pk2(bflo(ka.w) * da, bflo(kb.w) * db); d[7 * (STT / 2)] = pk2(bfhi(ka.w) * da, bfhi(kb.w) * db); } }
	v_cndmask_b32_e32 v8, 0, v8, vcc
	v_cmp_ge_i32_e32 vcc, 17, v241
	v_cvt_pk_bf16_f32 v8, v8, s0
	ds_write_b16 v240, v8 offset:2304
	v_cndmask_b32_e32 v9, 0, v9, vcc
	v_cmp_ge_i32_e32 vcc, 18, v241
	v_cvt_pk_bf16_f32 v9, v9, s0
	ds_write_b16 v240, v9 offset:2448
	v_cndmask_b32_e32 v10, 0, v10, vcc
	v_cmp_ge_i32_e32 vcc, 19, v241
	v_cvt_pk_bf16_f32 v10, v10, s0
	ds_write_b16 v240, v10 offset:2592
	v_cndmask_b32_e32 v11, 0, v11, vcc
	v_cmp_ge_i32_e32 vcc, 24, v241
	v_cvt_pk_bf16_f32 v11, v11, s0
	ds_write_b16 v240, v11 offset:2736
	v_cndmask_b32_e32 v12, 0, v12, vcc
	v_cmp_ge_i32_e32 vcc, 25, v241
	v_cvt_pk_bf16_f32 v12, v12, s0
	ds_write_b16 v240, v12 offset:3456
	v_cndmask_b32_e32 v13, 0, v13, vcc
	v_cmp_ge_i32_e32 vcc, 26, v241
	v_cvt_pk_bf16_f32 v13, v13, s0
	ds_write_b16 v240, v13 offset:3600
	v_cndmask_b32_e32 v14, 0, v14, vcc
	v_cmp_ge_i32_e32 vcc, 27, v241
	v_cvt_pk_bf16_f32 v14, v14, s0
	ds_write_b16 v240, v14 offset:3744
	v_cndmask_b32_e32 v15, 0, v15, vcc
	v_cvt_pk_bf16_f32 v15, v15, s0
	ds_write_b16 v240, v15 offset:3888
	v_ashrrev_i32_e32 v4, 2, v64
	v_mad_u32_u24 v11, v50, s75, 0
	v_and_b32_e32 v14, -8, v4
	v_lshl_add_u32 v6, v14, 1, v11
	v_lshl_add_u32 v5, v50, 3, s77
	ds_read_b128 v[0:3], v6 offset:17680
	ds_read_b128 v[6:9], v6 offset:17408
	ds_read_b64 v[12:13], v5 offset:1024
	v_lshl_add_u32 v10, v50, 2, s76
	v_mad_u64_u32 v[14:15], s[6:7], v14, s74, v[10:11]
	s_waitcnt lgkmcnt(2)
	v_lshlrev_b32_e32 v67, 16, v0
	s_waitcnt lgkmcnt(1)
	v_lshlrev_b32_e32 v66, 16, v6
	s_waitcnt lgkmcnt(0)
	v_pk_mul_f32 v[66:67], v[12:13], v[66:67]
	s_nop 0
	v_cvt_pk_bf16_f32 v5, v66, v67
	v_and_b32_e32 v67, 0xffff0000, v0
	v_and_b32_e32 v66, 0xffff0000, v6
	v_pk_mul_f32 v[66:67], v[12:13], v[66:67]
	s_nop 0
	v_cvt_pk_bf16_f32 v0, v66, v67
	ds_write2_b32 v14, v5, v0 offset1:36
	v_lshlrev_b32_e32 v67, 16, v1
	v_lshlrev_b32_e32 v66, 16, v7
	v_and_b32_e32 v1, 0xffff0000, v1
	v_and_b32_e32 v0, 0xffff0000, v7
	v_pk_mul_f32 v[66:67], v[12:13], v[66:67]
	v_pk_mul_f32 v[0:1], v[12:13], v[0:1]
	v_cvt_pk_bf16_f32 v5, v66, v67
	v_cvt_pk_bf16_f32 v0, v0, v1
	ds_write2_b32 v14, v5, v0 offset0:72 offset1:108
	v_lshlrev_b32_e32 v1, 16, v2
	v_lshlrev_b32_e32 v0, 16, v8
	v_pk_mul_f32 v[0:1], v[12:13], v[0:1]
	s_nop 0
	v_cvt_pk_bf16_f32 v5, v0, v1
	v_and_b32_e32 v1, 0xffff0000, v2
	v_and_b32_e32 v0, 0xffff0000, v8
	v_pk_mul_f32 v[0:1], v[12:13], v[0:1]
	s_nop 0
	v_cvt_pk_bf16_f32 v0, v0, v1
	ds_write2_b32 v14, v5, v0 offset0:144 offset1:180
	v_lshlrev_b32_e32 v1, 16, v3
	v_lshlrev_b32_e32 v0, 16, v9
	v_pk_mul_f32 v[0:1], v[12:13], v[0:1]
	s_nop 0
	v_cvt_pk_bf16_f32 v2, v0, v1
	v_and_b32_e32 v1, 0xffff0000, v3
	v_and_b32_e32 v0, 0xffff0000, v9
	v_pk_mul_f32 v[0:1], v[12:13], v[0:1]
	s_nop 0
	v_cvt_pk_bf16_f32 v0, v0, v1
	ds_write2_b32 v14, v2, v0 offset0:216 offset1:252
	v_ashrrev_i32_e32 v0, 2, v63
	v_and_b32_e32 v5, -8, v0
	v_lshl_add_u32 v6, v5, 1, v11
	ds_read_b128 v[0:3], v6 offset:17680
	ds_read_b128 v[6:9], v6 offset:17408
	v_mad_u64_u32 v[10:11], s[6:7], v5, s74, v[10:11]
	s_waitcnt lgkmcnt(1)
	v_lshlrev_b32_e32 v15, 16, v0
	s_waitcnt lgkmcnt(0)
	v_lshlrev_b32_e32 v14, 16, v6
	v_pk_mul_f32 v[14:15], v[12:13], v[14:15]
	s_nop 0
	v_cvt_pk_bf16_f32 v5, v14, v15
	v_and_b32_e32 v15, 0xffff0000, v0
	v_and_b32_e32 v14, 0xffff0000, v6
	v_pk_mul_f32 v[14:15], v[12:13], v[14:15]
	s_nop 0
	v_cvt_pk_bf16_f32 v0, v14, v15
	ds_write2_b32 v10, v5, v0 offset1:36
	v_lshlrev_b32_e32 v15, 16, v1
	v_lshlrev_b32_e32 v14, 16, v7
	v_and_b32_e32 v1, 0xffff0000, v1
	v_and_b32_e32 v0, 0xffff0000, v7
	v_pk_mul_f32 v[14:15], v[12:13], v[14:15]
	v_pk_mul_f32 v[0:1], v[12:13], v[0:1]
	v_cvt_pk_bf16_f32 v5, v14, v15
	v_cvt_pk_bf16_f32 v0, v0, v1
	ds_write2_b32 v10, v5, v0 offset0:72 offset1:108
	v_lshlrev_b32_e32 v1, 16, v2
	v_lshlrev_b32_e32 v0, 16, v8
	v_pk_mul_f32 v[0:1], v[12:13], v[0:1]
	s_nop 0
	v_cvt_pk_bf16_f32 v5, v0, v1
	v_and_b32_e32 v1, 0xffff0000, v2
	v_and_b32_e32 v0, 0xffff0000, v8
	v_pk_mul_f32 v[0:1], v[12:13], v[0:1]
	s_nop 0
	v_cvt_pk_bf16_f32 v0, v0, v1
	ds_write2_b32 v10, v5, v0 offset0:144 offset1:180
	v_lshlrev_b32_e32 v1, 16, v3
	v_lshlrev_b32_e32 v0, 16, v9
	v_pk_mul_f32 v[0:1], v[12:13], v[0:1]
	v_and_b32_e32 v5, 3, v65
	v_cvt_pk_bf16_f32 v2, v0, v1
	v_and_b32_e32 v1, 0xffff0000, v3
	v_and_b32_e32 v0, 0xffff0000, v9
	v_pk_mul_f32 v[0:1], v[12:13], v[0:1]
	v_lshl_add_u32 v65, v5, 7, s77
	v_cvt_pk_bf16_f32 v0, v0, v1
	ds_write2_b32 v10, v2, v0 offset0:216 offset1:252
	v_mul_lo_u32 v0, v4, s50
	v_lshlrev_b32_e32 v1, 6, v5
	s_waitcnt lgkmcnt(0)
	s_barrier
; DI float bflo(unsigned u) { return __uint_as_float(u << 16); }
; DI float bfhi(unsigned u) { return __uint_as_float(u & 0xffff0000u); }
; template <bool CONS>
; DI void ml_chain_role(const Params& p, unsigned char* smem, int dir, int b, int h) {
;     ...
;             { const int i = t >> 2, part = t & 3; float qn = 0.f, rs = 0.f;
; #pragma unroll
;               for (int q = 0; q < 4; ++q) { const u32x4 qv = *(const u32x4*)(sQ + i * ST + part * 32 + 8 * q);
;                   const f32x4 n0 = *(const f32x4*)(sN + part * 32 + 8 * q), n1 = *(const f32x4*)(sN + part * 32 + 8 * q + 4);
;                   qn += (bflo(qv.x) * n0.x + bfhi(qv.x) * n0.y) + (bflo(qv.y) * n0.z + bfhi(qv.y) * n0.w) + (bflo(qv.z) * n1.x + bfhi(qv.z) * n1.y) + (bflo(qv.w) * n1.z + bfhi(qv.w) * n1.w); }
; #pragma unroll
;               for (int q = 0; q < 2; ++q) { const u32x4 sv = *(const u32x4*)(sS + i * STT + part * 16 + 8 * q);
;                   rs += (bflo(sv.x) + bfhi(sv.x)) + (bflo(sv.y) + bfhi(sv.y)) + (bflo(sv.z) + bfhi(sv.z)) + (bflo(sv.w) + bfhi(sv.w)); }
;               qn += __shfl_xor(qn, 1); qn += __shfl_xor(qn, 2); rs += __shfl_xor(rs, 1); rs += __shfl_xor(rs, 2);
;               if (part == 0) { const float den = sWin[i] * qn + rs; sRden[i] = 1.f / fmaxf(fabsf(den), sFloor[i]); } }
	v_add3_u32 v14, 0, v0, v1
	ds_read_b128 v[0:3], v14
	ds_read_b128 v[6:9], v14 offset:16
	ds_read_b128 v[10:13], v14 offset:32
	ds_read_b128 v[66:69], v14 offset:48
	ds_read_b128 v[70:73], v65 offset:1792
	ds_read_b128 v[74:77], v65 offset:1808
	ds_read_b128 v[78:81], v65 offset:1824
	ds_read_b128 v[82:85], v65 offset:1840
	s_waitcnt lgkmcnt(7)
	v_and_b32_e32 v15, 0xffff0000, v1
	v_lshlrev_b32_e32 v14, 16, v1
	s_waitcnt lgkmcnt(3)
	v_mul_f32_e32 v50, v73, v15
	v_pk_fma_f32 v[14:15], v[72:73], v[14:15], v[50:51] op_sel_hi:[1,1,0]
	v_lshlrev_b32_e32 v73, 16, v0
	v_mov_b32_e32 v87, v70
	v_and_b32_e32 v1, 0xffff0000, v0
	v_and_b32_e32 v0, 0xffff0000, v2
	s_waitcnt lgkmcnt(2)
	v_mov_b32_e32 v70, v75
	v_lshlrev_b32_e32 v72, 16, v2
	v_mov_b32_e32 v86, v74
	v_pk_mul_f32 v[0:1], v[70:71], v[0:1]
	v_lshlrev_b32_e32 v53, 5, v5
	v_pk_fma_f32 v[0:1], v[86:87], v[72:73], v[0:1]
	s_waitcnt lgkmcnt(1)
	v_mov_b32_e32 v73, v78
	v_pk_add_f32 v[14:15], v[0:1], v[14:15] op_sel:[1,0] op_sel_hi:[0,1]
	v_pk_add_f32 v[14:15], v[0:1], v[14:15]
	v_lshlrev_b32_e32 v0, 16, v3
	v_and_b32_e32 v1, 0xffff0000, v3
	v_mul_f32_e32 v2, v76, v0
	v_pk_fma_f32 v[70:71], v[76:77], v[0:1], v[2:3] op_sel_hi:[1,1,0]
	v_and_b32_e32 v1, 0xffff0000, v7
	v_lshlrev_b32_e32 v0, 16, v7
	v_mul_f32_e32 v2, v81, v1
	v_pk_fma_f32 v[0:1], v[80:81], v[0:1], v[2:3] op_sel_hi:[1,1,0]
	v_lshlrev_b32_e32 v3, 16, v6
	v_and_b32_e32 v7, 0xffff0000, v6
	v_and_b32_e32 v6, 0xffff0000, v8
	s_waitcnt lgkmcnt(0)
	v_mov_b32_e32 v78, v83
	v_lshlrev_b32_e32 v2, 16, v8
	v_mov_b32_e32 v72, v82
	v_pk_mul_f32 v[6:7], v[78:79], v[6:7]
	v_and_b32_e32 v77, 0xffff0000, v11
	v_pk_fma_f32 v[2:3], v[72:73], v[2:3], v[6:7]
	v_lshlrev_b32_e32 v6, 16, v9
	v_pk_add_f32 v[0:1], v[2:3], v[0:1] op_sel:[1,0] op_sel_hi:[0,1]
	v_pk_add_f32 v[72:73], v[2:3], v[0:1]
	v_and_b32_e32 v7, 0xffff0000, v9
	v_mul_f32_e32 v8, v84, v6
	ds_read_b128 v[0:3], v65 offset:1856
	v_pk_fma_f32 v[74:75], v[84:85], v[6:7], v[8:9] op_sel_hi:[1,1,0]
	ds_read_b128 v[6:9], v65 offset:1872
	v_lshlrev_b32_e32 v76, 16, v11
	v_and_b32_e32 v11, 0xffff0000, v10
	s_waitcnt lgkmcnt(1)
	v_mul_f32_e32 v50, v3, v77
	v_pk_fma_f32 v[2:3], v[2:3], v[76:77], v[50:51] op_sel_hi:[1,1,0]
	v_lshlrev_b32_e32 v77, 16, v10
	v_mov_b32_e32 v79, v0
	v_and_b32_e32 v10, 0xffff0000, v12
	s_waitcnt lgkmcnt(0)
	v_mov_b32_e32 v0, v7
	v_lshlrev_b32_e32 v76, 16, v12
	v_mov_b32_e32 v78, v6
	v_pk_mul_f32 v[0:1], v[0:1], v[10:11]
	v_lshlrev_b32_e32 v6, 16, v13
	v_pk_fma_f32 v[0:1], v[78:79], v[76:77], v[0:1]
	v_and_b32_e32 v7, 0xffff0000, v13
	v_pk_add_f32 v[2:3], v[0:1], v[2:3] op_sel:[1,0] op_sel_hi:[0,1]
	v_pk_add_f32 v[10:11], v[0:1], v[2:3]
	ds_read_b128 v[0:3], v65 offset:1888
	v_mul_f32_e32 v12, v8, v6
	v_pk_fma_f32 v[12:13], v[8:9], v[6:7], v[12:13] op_sel_hi:[1,1,0]
	ds_read_b128 v[6:9], v65 offset:1904
	v_lshlrev_b32_e32 v76, 16, v66
	v_and_b32_e32 v77, 0xffff0000, v66
	s_waitcnt lgkmcnt(1)
	v_mul_f32_e32 v12, v0, v76
	v_pk_fma_f32 v[76:77], v[0:1], v[76:77], v[12:13] op_sel_hi:[1,1,0]
	v_lshlrev_b32_e32 v0, 16, v67
	v_and_b32_e32 v1, 0xffff0000, v67
	v_mul_f32_e32 v12, v2, v0
	v_pk_fma_f32 v[66:67], v[2:3], v[0:1], v[12:13] op_sel_hi:[1,1,0]
	v_lshlrev_b32_e32 v0, 16, v68
	s_waitcnt lgkmcnt(0)
	v_mul_f32_e32 v79, v6, v0
	v_and_b32_e32 v0, 0xffff0000, v68
	v_mul_f32_e32 v11, v7, v0
	v_mul_lo_u32 v0, v4, s74
	v_lshlrev_b32_e32 v6, 16, v69
	v_add3_u32 v15, s73, v0, v53
	ds_read_b128 v[0:3], v15
	v_and_b32_e32 v7, 0xffff0000, v69
	v_mul_f32_e32 v12, v8, v6
	v_pk_fma_f32 v[68:69], v[8:9], v[6:7], v[12:13] op_sel_hi:[1,1,0]
	ds_read_b128 v[6:9], v15 offset:16
	s_waitcnt lgkmcnt(1)
	v_lshlrev_b32_e32 v12, 16, v2
	v_and_b32_e32 v2, 0xffff0000, v2
	v_add_f32_e32 v78, v12, v2
	v_lshlrev_b32_e32 v76, 16, v3
	v_and_b32_e32 v66, 0xffff0000, v3
	s_waitcnt lgkmcnt(0)
	v_lshlrev_b32_e32 v70, 16, v6
	v_and_b32_e32 v2, 0xffff0000, v6
	v_lshlrev_b32_e32 v3, 16, v7
	v_and_b32_e32 v6, 0xffff0000, v7
	v_and_b32_e32 v7, 64, v59
	v_add_f32_e32 v50, v3, v6
	v_xor_b32_e32 v3, 1, v59
	v_add_u32_e32 v15, 64, v7
	v_lshlrev_b32_e32 v81, 16, v1
	v_lshlrev_b32_e32 v80, 16, v0
	v_and_b32_e32 v1, 0xffff0000, v1
	v_and_b32_e32 v0, 0xffff0000, v0
	v_cmp_lt_i32_e32 vcc, v3, v15
	v_pk_add_f32 v[0:1], v[80:81], v[0:1]
	v_lshlrev_b32_e32 v74, 16, v8
	v_cndmask_b32_e32 v3, v59, v3, vcc
	v_lshlrev_b32_e32 v53, 2, v3
	v_pk_add_f32 v[0:1], v[0:1], v[0:1] op_sel:[0,1] op_sel_hi:[1,0]
	v_mov_b32_e32 v3, v14
	v_and_b32_e32 v6, 0xffff0000, v8
	v_mov_b32_e32 v1, v11
	v_pk_add_f32 v[2:3], v[70:71], v[2:3]
	v_mov_b32_e32 v7, v72
	v_lshlrev_b32_e32 v12, 16, v9
	v_and_b32_e32 v8, 0xffff0000, v9
	v_pk_add_f32 v[0:1], v[78:79], v[0:1]
	v_pk_add_f32 v[66:67], v[76:77], v[66:67]
	v_pk_add_f32 v[6:7], v[74:75], v[6:7]
	v_mov_b32_e32 v9, v10
	v_pk_add_f32 v[2:3], v[2:3], v[50:51]
	v_pk_add_f32 v[0:1], v[0:1], v[66:67]
	v_mov_b32_e32 v68, v51
	v_pk_add_f32 v[8:9], v[12:13], v[8:9]
	v_pk_add_f32 v[2:3], v[2:3], v[6:7]
	v_pk_add_f32 v[0:1], v[0:1], v[68:69]
	v_pk_add_f32 v[2:3], v[2:3], v[8:9]
	v_xor_b32_e32 v6, 2, v59
	v_pk_add_f32 v[0:1], v[2:3], v[0:1]
	ds_bpermute_b32 v3, v53, v1
	ds_bpermute_b32 v2, v53, v0
	v_cmp_lt_i32_e32 vcc, v6, v15
	s_waitcnt lgkmcnt(0)
	v_pk_add_f32 v[0:1], v[0:1], v[2:3]
	v_cndmask_b32_e32 v6, v59, v6, vcc
	v_lshlrev_b32_e32 v6, 2, v6
	ds_bpermute_b32 v3, v6, v1
	ds_bpermute_b32 v2, v6, v0
	v_cmp_eq_u32_e32 vcc, 0, v5
	s_and_saveexec_b64 s[6:7], vcc
	s_cbranch_execz .LBB0_472
	v_lshl_add_u32 v6, v4, 2, s77
	ds_read2st64_b32 v[4:5], v6 offset0:2 offset1:3
	s_waitcnt lgkmcnt(1)
	v_pk_add_f32 v[0:1], v[0:1], v[2:3]
	s_waitcnt lgkmcnt(0)
	v_fmac_f32_e32 v0, v1, v4
	v_max_f32_e32 v1, v5, v5
	v_max_f32_e64 v0, |v0|, v1
	v_div_scale_f32 v1, s[8:9], v0, v0, 1.0
	v_rcp_f32_e32 v2, v1
	v_div_scale_f32 v3, vcc, 1.0, v0, 1.0
	v_fma_f32 v4, -v1, v2, 1.0
	v_fmac_f32_e32 v2, v4, v2
	v_mul_f32_e32 v4, v3, v2
	v_fma_f32 v5, -v1, v4, v3
	v_fmac_f32_e32 v4, v5, v2
	v_fma_f32 v1, -v1, v4, v3
	v_div_fmas_f32 v1, v1, v2, v4
	v_div_fixup_f32 v0, v1, v0, 1.0
	ds_write_b32 v6, v0 offset:1280
